# S5 pass B hint block also touches the sample steps' u rows (both iterations) one block ahead
# speedup vs baseline: 1.0022x; 1.0022x over previous
; __device__ __forceinline__ int opq(int v) { asm volatile("" : "+v"(v)); return v; }
; __device__ __forceinline__ void ssm_stage_load(const Args& a, size_t row0, int ntok, int gq, u32x4 (&pre)[2]) {
;     const int tid = opq(threadIdx.x); const bf16_t* Z = (const bf16_t*)(a.ws + WS_C);
; #pragma unroll
;     for (int k = 0; k < 2; ++k) { const int idx = tid + 512 * k, t = idx >> 4, c8 = idx & 15; if (idx < ntok * 16) pre[k] = *(const u32x4*)(Z + (row0 + t) * INC + ZU + gq * 128 + c8 * 8); }
; }
; __global__ void __launch_bounds__(512, 2) mk_fwd(Args a) {
;     ...
;             for (int v = bx; v < DEC_B * 4; v += G) { const int gq = v & 3, b = v >> 2; const int lane = opq(threadIdx.x) & 63, g = gq * 8 + wave;
;                 const size_t so = ((size_t)l * DEC_B + b) * NG * NP + g * NP + lane;
;                 ssm_stage_load(a, (size_t)NTOK_P + b * DEC_T, DEC_T, gq, pre);
;                 float hr = a.in[I_SR][so], hi = a.in[I_SI][so];
;                 ssm_unit<true>(a, lds, T, pre, l, (size_t)NTOK_P + b * DEC_T, DEC_T, gq, hr, hi, wave);
.LBB0_472:
	s_add_u32 s6, s6, 0x10000
	s_addc_u32 s7, s7, 0
	s_cmp_eq_u32 s12, 3
	s_cbranch_scc0 .Lssp_skip
	v_readlane_b32 s98, v255, 41
	s_and_b32 s99, s2, 0xff
	s_lshl_b32 s98, s98, 18
	s_lshr_b32 s100, s99, 2
	s_and_b32 s99, s99, 3
	s_lshl_b32 s100, s100, 11
	s_lshl_b32 s99, s99, 9
	s_add_i32 s98, s98, s100
	s_add_i32 s98, s98, s99
	v_add_u32_e32 v236, s98, v184
	v_lshlrev_b32_e32 v236, 2, v236
	v_mov_b32_e32 v237, 0
	v_readlane_b32 s98, v252, 8
	v_readlane_b32 s99, v252, 9
	v_readlane_b32 s100, v252, 10
	v_readlane_b32 s101, v252, 11
	s_nop 1
	v_lshl_add_u64 v[238:239], s[98:99], 0, v[236:237]
	v_lshl_add_u64 v[240:241], s[100:101], 0, v[236:237]
	global_load_dword v242, v[238:239], off
	global_load_dword v243, v[240:241], off
	v_add_u32_e32 v236, 0x80000, v236
	v_lshl_add_u64 v[238:239], s[98:99], 0, v[236:237]
	v_lshl_add_u64 v[240:241], s[100:101], 0, v[236:237]
	global_load_dword v244, v[238:239], off
	global_load_dword v245, v[240:241], off
	v_and_b32_e32 v246, 63, v184
	v_lshrrev_b32_e32 v247, 4, v246
	v_and_b32_e32 v246, 15, v246
	s_and_b32 s98, s2, 0xfc
	s_add_i32 s98, s98, 0x4000
	v_add_u32_e32 v247, s98, v247
	v_mul_u32_u24_e32 v247, 0x1a00, v247
	s_and_b32 s99, s2, 3
	s_lshl_b32 s99, s99, 8
	s_addk_i32 s99, 0x600
	v_lshl_add_u32 v246, v246, 4, v247
	v_add_u32_e32 v246, s99, v246
	v_mov_b32_e32 v247, 0
	s_add_u32 s100, s70, 0x7b00000
	s_addc_u32 s101, s71, 0
	v_lshl_add_u64 v[248:249], s[100:101], 0, v[246:247]
	global_load_dword v244, v[248:249], off
	s_add_u32 s100, s100, 0x1a0000
	s_addc_u32 s101, s101, 0
	v_lshl_add_u64 v[248:249], s[100:101], 0, v[246:247]
	global_load_dword v245, v[248:249], off
